# dynamic work distribution: differential-attention items claimed from a per-XCD-group queue with a returning atomic (largest query blocks first) instead of the static 8-per-workgroup split
# baseline (speedup 1.0000x reference)
; __device__ __forceinline__ void phase_odd_attn(const int wid_s, CParams& p, int j, int layer, LAS unsigned char* lds) {
;     ...
;         {
; #pragma unroll 1
;             for (int i = 0; i < 8; ++i) { const int bh = xcd * 8 + i, b = bh >> 2, h = bh & 3; const int base = (kx + 8 * (i >> 1)) & 31; const int qb = (i & 1) ? (31 - base) : base;
;                 diff_attn_item(p, j, layer, lds, b, h, qb, tid, lane, wave); __syncthreads(); }
.LBB0_593:
	s_lshl_b32 s34, s76, 13
	s_mov_b32 s77, s96
	s_mov_b32 s71, s81
	s_branch .Ldq_fetch

; __device__ __forceinline__ void phase_odd_attn(const int wid_s, CParams& p, int j, int layer, LAS unsigned char* lds) {
;     ...
;             for (int i = 0; i < 8; ++i) { const int bh = xcd * 8 + i, b = bh >> 2, h = bh & 3; const int base = (kx + 8 * (i >> 1)) & 31; const int qb = (i & 1) ? (31 - base) : base;
;                 diff_attn_item(p, j, layer, lds, b, h, qb, tid, lane, wave); __syncthreads(); }
.Ldq_fetch:
	v_cmp_eq_u32_e32 vcc, 0, v161
	s_and_saveexec_b64 s[4:5], vcc
	s_cbranch_execz .Ldq_nof
	v_readlane_b32 s6, v253, 1
	v_readlane_b32 s7, v253, 2
	s_nop 0
	s_load_dwordx2 s[6:7], s[6:7], 0xc8
	v_mov_b32_e32 v66, 1
	v_mov_b32_e32 v67, 0x23f00
	s_lshl_b32 s12, s76, 2
	s_waitcnt lgkmcnt(0)
	s_add_u32 s6, s6, 0xe781104
	s_addc_u32 s7, s7, 0
	s_add_u32 s6, s6, s12
	s_addc_u32 s7, s7, 0
	global_atomic_add v66, v1, v66, s[6:7] sc0
	s_waitcnt vmcnt(0)
	ds_write_b32 v67, v66
.Ldq_nof:
	s_or_b64 exec, exec, s[4:5]
	s_waitcnt lgkmcnt(0)
	s_barrier
	v_mov_b32_e32 v67, 0x23f00
	ds_read_b32 v66, v67
	s_waitcnt lgkmcnt(0)
	v_readfirstlane_b32 s6, v66
	s_cmp_ge_u32 s6, 0x120
	s_cselect_b32 s7, 0x120, 0
	s_sub_u32 s6, s6, s7
	s_cmp_ge_u32 s6, 0x100
	s_cbranch_scc1 .Ldq_done
	s_lshr_b32 s35, s6, 5
	s_and_b32 s6, s6, 31
	s_sub_u32 s100, 31, s6
	s_branch .LBB0_595
.Ldq_done:
	s_getpc_b64 s[98:99]

; __device__ __forceinline__ void diff_attn_item(CParams& p, int j, int layer, LAS unsigned char* lds, int b, int h, int qb, int tid_in, int lane_in, int wave) {
;     ...
;     const int mp = wave >> 2, qs = wave & 3, r = lane & 31, hh = lane >> 5;
;     const int tb0 = b * SEQ; const int q0 = qb * 128 + 32 * qs;
;     if (tid < 129) bdl[tid] = bd[tid];
;     h16x8 qf[4];
; #pragma unroll
;     for (int s = 0; s < 4; ++s) qf[s] = *(const h16x8*)(proj + (size_t)(tb0 + q0 + r) * OD_N + h * 128 + mp * 64 + 16 * s + 8 * hh);
;     f32x16 o[4];
; #pragma unroll
;     for (int d = 0; d < 4; ++d)
; #pragma unroll
;         for (int i = 0; i < 16; ++i) o[d][i] = 0.f;
;     float m_run = -INFINITY, l_run = 0.f;
;     const int qp = q0 + r;
;     const int vlo = r * 72 + ((hh ^ (r >> 3)) << 2), vhi = r * 72 + (((hh ^ (r >> 3)) ^ 2) << 2);
;     const int nkt = 2 * (qb + 1);
;     h16x8 pk[2], pv[2];
; #pragma unroll
;     for (int i = 0; i < 2; ++i) { const int key = i * 32 + (tid >> 4), ch = tid & 15;
;         pk[i] = *(const h16x8*)(proj + (size_t)(tb0 + key) * OD_N + 512 + h * 128 + ch * 8);
;         pv[i] = *(const h16x8*)(proj + (size_t)(tb0 + key) * OD_N + 1024 + h * 128 + ch * 8); }
;     ...
;     ATT_STAGE(0, 512 + h * 128, 1024 + h * 128, 1);
;     __syncthreads();
; __device__ __forceinline__ void phase_odd_attn(const int wid_s, CParams& p, int j, int layer, LAS unsigned char* lds) {
;     ...
;             for (int i = 0; i < 8; ++i) { const int bh = xcd * 8 + i, b = bh >> 2, h = bh & 3; const int base = (kx + 8 * (i >> 1)) & 31; const int qb = (i & 1) ? (31 - base) : base;
.LBB0_597:
	s_or_b64 exec, exec, s[4:5]
	s_lshl_b32 s4, s35, 2
	s_and_b32 s4, s4, 24
	s_add_i32 s4, s4, s73
	s_and_b32 s4, s4, 31
	s_and_b32 s5, s35, 1
	s_xor_b32 s6, s4, 31
	s_cmp_eq_u32 s5, 0
	s_cselect_b32 s6, s4, s6
	s_mov_b32 s6, s100
	s_lshl_b32 s4, s35, 10
	s_and_b32 s4, s4, 0x1000
	s_or_b32 s7, s4, s34
	v_ashrrev_i32_e32 v3, 4, v2
	v_add_u32_e32 v200, s7, v3
	v_lshlrev_b32_e32 v0, 4, v2
	s_lshl_b32 s30, s6, 7
	v_mov_b64_e32 v[20:21], s[14:15]
	v_and_b32_e32 v22, 0xf0, v0
	v_add_u32_e32 v0, 32, v200
	v_and_b32_e32 v198, 31, v2
	v_or_b32_e32 v199, s30, v186
	s_lshl_b32 s58, s12, 8
	v_mad_i64_i32 v[4:5], s[4:5], v200, s33, v[20:21]
	v_mad_i64_i32 v[12:13], s[4:5], v0, s33, v[20:21]
	s_lshl_b32 s36, s12, 7
	s_lshl_b32 s37, s6, 1
	v_or3_b32 v0, s7, v198, v199
	s_add_u32 s4, s14, s58
	v_mad_u64_u32 v[20:21], s[12:13], v0, s33, v[20:21]
	v_bfe_u32 v30, v2, 5, 1
	s_addc_u32 s5, s15, 0
	v_lshl_add_u64 v[20:21], v[20:21], 0, s[58:59]
	v_lshl_add_u64 v[4:5], v[4:5], 0, s[58:59]
	v_mov_b32_e32 v23, v1
	v_lshl_add_u64 v[12:13], v[12:13], 0, s[58:59]
	v_mov_b32_e32 v25, v1
	v_lshlrev_b32_e32 v24, 4, v30
	v_add_u32_e32 v28, 64, v200
	v_add_u32_e32 v31, 0x60, v200
	v_mov_b64_e32 v[26:27], s[4:5]
	v_lshl_add_u64 v[20:21], v[140:141], 1, v[20:21]
	v_lshl_add_u64 v[8:9], v[4:5], 0, v[22:23]
	v_lshl_add_u64 v[16:17], v[12:13], 0, v[22:23]
	v_mad_i64_i32 v[28:29], s[12:13], v28, s33, v[26:27]
	v_mad_i64_i32 v[26:27], s[12:13], v31, s33, v[26:27]
	v_lshl_add_u64 v[20:21], v[20:21], 0, v[24:25]
	global_load_dwordx4 v[4:7], v[8:9], off offset:1024
	s_nop 0
	global_load_dwordx4 v[8:11], v[8:9], off offset:2048
	s_nop 0
	global_load_dwordx4 v[12:15], v[16:17], off offset:1024
	s_nop 0
	global_load_dwordx4 v[16:19], v[16:17], off offset:2048
	v_lshl_add_u64 v[28:29], v[28:29], 0, v[22:23]
	v_lshl_add_u64 v[26:27], v[26:27], 0, v[22:23]
	global_load_dwordx4 v[110:113], v[20:21], off
	global_load_dwordx4 v[106:109], v[20:21], off offset:32
	global_load_dwordx4 v[102:105], v[20:21], off offset:64
	global_load_dwordx4 v[98:101], v[20:21], off offset:96
	global_load_dwordx4 v[126:129], v[28:29], off offset:1024
	global_load_dwordx4 v[118:121], v[28:29], off offset:2048
	global_load_dwordx4 v[122:125], v[26:27], off offset:1024
	global_load_dwordx4 v[114:117], v[26:27], off offset:2048
	v_and_b32_e32 v193, 63, v2
	v_bfe_u32 v20, v2, 3, 2
	v_and_b32_e32 v2, 15, v2
	v_lshlrev_b32_e32 v21, 2, v2
	v_lshlrev_b32_e32 v25, 1, v3
	v_lshl_add_u32 v202, v2, 4, 0
	v_mul_lo_u32 v203, v3, s97
	v_mul_u32_u24_e32 v204, 0x480, v2
	v_and_b32_e32 v25, 6, v25
	v_bfe_u32 v26, v3, 2, 1
	v_bfe_u32 v27, v3, 3, 1
	v_and_b32_e32 v2, -13, v3
	v_lshl_or_b32 v2, v26, 3, v2
	v_lshl_or_b32 v26, v27, 2, v2
	v_and_b32_e32 v21, 0x38, v21
	v_add_u32_e32 v2, 32, v26
	v_bitop3_b32 v3, v26, v21, -4 bitop3:0x6c
	v_bitop3_b32 v2, v2, v21, -4 bitop3:0x6c
	v_add_u32_e32 v205, 0, v25
	v_lshlrev_b32_e32 v206, 1, v3
	v_add_u32_e32 v27, v202, v203
	v_lshlrev_b32_e32 v207, 1, v2
	v_add3_u32 v2, v205, v206, v204
	v_xor_b32_e32 v20, v30, v20
	v_lshlrev_b32_e32 v26, 2, v20
	v_lshlrev_b32_e32 v192, 2, v30
	v_xor_b32_e32 v194, 8, v26
	v_add_u32_e32 v208, v187, v24
	v_bfe_u32 v196, v193, 4, 1
	v_xor_b32_e32 v196, v30, v196
	v_lshlrev_b32_e32 v196, 4, v196
	s_waitcnt vmcnt(29)
	v_lshl_add_u64 v[130:131], s[4:5], 0, v[22:23]
	v_mov_b32_e32 v3, v1
	s_mov_b32 s38, 0
	s_or_b32 s39, s37, 1
	v_or_b32_e32 v210, 31, v199
	v_mad_u32_u24 v195, v198, s60, 0
	v_mul_u32_u24_e32 v209, 0x110, v198
	v_mad_u32_u24 v211, v198, s97, v208
	v_mov_b32_e32 v197, 0
	v_mov_b32_e32 v201, 0xff800000
	s_movk_i32 s40, 0xbf
	s_waitcnt vmcnt(11)
	ds_write_b128 v27, v[4:7]
	s_waitcnt vmcnt(10)
	ds_write_b16 v2, v8 offset:34816
	ds_write_b16_d16_hi v2, v8 offset:34960
	ds_write_b16 v2, v9 offset:35104
	ds_write_b16_d16_hi v2, v9 offset:35248
	ds_write_b16 v2, v10 offset:35392
	ds_write_b16_d16_hi v2, v10 offset:35536
	ds_write_b16 v2, v11 offset:35680
	ds_write_b16_d16_hi v2, v11 offset:35824
	s_waitcnt vmcnt(9)
	ds_write_b128 v27, v[12:15] offset:8704
	v_add3_u32 v2, v205, v207, v204
	s_waitcnt vmcnt(8)
	ds_write_b16 v2, v16 offset:34816
	ds_write_b16_d16_hi v2, v16 offset:34960
	ds_write_b16 v2, v17 offset:35104
	ds_write_b16_d16_hi v2, v17 offset:35248
	ds_write_b16 v2, v18 offset:35392
	ds_write_b16_d16_hi v2, v18 offset:35536
	ds_write_b16 v2, v19 offset:35680
	ds_write_b16_d16_hi v2, v19 offset:35824
	v_add3_u32 v2, v191, s30, v198
	v_mov_b32_e32 v16, v1
	v_mov_b32_e32 v17, v1
	v_sub_u32_e32 v212, v2, v192
	v_mov_b32_e32 v2, v1
	v_mov_b32_e32 v4, v1
	v_mov_b32_e32 v5, v1
	v_mov_b32_e32 v6, v1
	v_mov_b32_e32 v7, v1
	v_mov_b32_e32 v8, v1
	v_mov_b32_e32 v9, v1
	v_mov_b32_e32 v10, v1
	v_mov_b32_e32 v11, v1
	v_mov_b32_e32 v12, v1
	v_mov_b32_e32 v13, v1
	v_mov_b32_e32 v14, v1
	v_mov_b32_e32 v15, v1
	v_mov_b64_e32 v[32:33], v[16:17]
	v_mov_b64_e32 v[48:49], v[16:17]
	v_mov_b64_e32 v[64:65], v[16:17]
	v_mov_b64_e32 v[30:31], v[14:15]
	v_mov_b64_e32 v[28:29], v[12:13]
	v_mov_b64_e32 v[26:27], v[10:11]
	v_mov_b64_e32 v[24:25], v[8:9]
	v_mov_b64_e32 v[22:23], v[6:7]
	v_mov_b64_e32 v[20:21], v[4:5]
	v_mov_b64_e32 v[18:19], v[2:3]
	v_mov_b64_e32 v[46:47], v[14:15]
	v_mov_b64_e32 v[44:45], v[12:13]
	v_mov_b64_e32 v[42:43], v[10:11]
	v_mov_b64_e32 v[40:41], v[8:9]
	v_mov_b64_e32 v[38:39], v[6:7]
	v_mov_b64_e32 v[36:37], v[4:5]
	v_mov_b64_e32 v[34:35], v[2:3]
	v_mov_b64_e32 v[62:63], v[14:15]
	v_mov_b64_e32 v[60:61], v[12:13]
	v_mov_b64_e32 v[58:59], v[10:11]
	v_mov_b64_e32 v[56:57], v[8:9]
	v_mov_b64_e32 v[54:55], v[6:7]
	v_mov_b64_e32 v[52:53], v[4:5]
	v_mov_b64_e32 v[50:51], v[2:3]
	s_waitcnt lgkmcnt(0)
	s_barrier
